# P6 ready6 counter replicated over 8 words (256 pollers no longer read one line)
# speedup vs baseline: 1.0020x; 1.0020x over previous
; __device__ __forceinline__ int fresh_tid() { int t = threadIdx.x; asm volatile("" : "+v"(t)); return t; }
;     const int tid = fresh_tid(), lane = tid & 63, gw = blockIdx.x * 8 + (tid >> 6), nw = (nblk ? nblk : (int)gridDim.x) * 8;
;     const float* mod = (const float*)(p.ws + WS_MOD); bf16_t* H = (bf16_t*)(p.ws + WS_H);
;     f32x4 gv[4];
; #pragma unroll
;     for (int i = 0; i < 4; ++i) gv[i] = *(const f32x4*)(g + (i >> 1) * 512 + lane * 8 + (i & 1) * 4);
;     for (int rowb = r0 + gw; rowb < r1; rowb += 4 * nw) {
;         f32x4 v[4][4];
; #pragma unroll
;         for (int q = 0; q < 4; ++q) { const int row = rowb + q * nw;
;             if (row < r1) { const float* src = from_out ? p.out + (size_t)row * DM : (row < NP ? p.x_prompt + (size_t)row * DM : p.x_sample + (size_t)(row - NP) * DM);
; __global__ __launch_bounds__(512, 2) void fwd_megakernel(Params p) {
;     ...
;     { unsigned* ready6 = (unsigned*)(p.ws + WS_CNT) + CNT_READY6 * 64;
;     ...
;       if (bid < 16) {
;           rownorm_phase<false, true>(p, p.g_ffn, 3072, 4096, true, NP, NTOK, 16);
.Lgb_ret_4:
.LBB0_633:
	s_or_b64 exec, exec, s[0:1]
	s_add_u32 s24, s58, 0xc944300
	s_addc_u32 s25, s59, 0
	s_cmp_lt_i32 s2, 16
	s_cselect_b64 s[20:21], -1, 0
	s_and_b64 vcc, exec, s[20:21]
	s_waitcnt lgkmcnt(0)
	s_barrier
	s_cbranch_vccz .LBB0_653
	v_mov_b32_e32 v17, v224
	s_movk_i32 s0, 0x4080
	v_ashrrev_i32_e32 v18, 6, v17
	v_add_u32_e32 v16, s97, v18
	v_cmp_gt_i32_e32 vcc, s0, v16
	s_and_saveexec_b64 s[36:37], vcc
	s_cbranch_execz .LBB0_649
	v_lshlrev_b32_e32 v0, 3, v17
	v_and_b32_e32 v64, 0x1f8, v0
	v_lshlrev_b32_e32 v19, 2, v64
	global_load_dwordx4 v[0:3], v19, s[28:29] offset:16
	global_load_dwordx4 v[4:7], v19, s[28:29]
	global_load_dwordx4 v[8:11], v19, s[28:29] offset:2064
	global_load_dwordx4 v[12:15], v19, s[28:29] offset:2048
	v_and_b32_e32 v17, 63, v17
	v_lshlrev_b32_e32 v68, 5, v17
	v_ashrrev_i32_e32 v17, 31, v16
	v_add_u32_e32 v21, s95, v18
	v_lshlrev_b64 v[18:19], 12, v[16:17]
	v_lshl_add_u64 v[70:71], s[56:57], 0, v[18:19]
	v_add_u32_e32 v18, 0x4180, v21
	s_mov_b64 s[0:1], 0x1a70000
	v_lshlrev_b64 v[16:17], 11, v[16:17]
	v_ashrrev_i32_e32 v19, 31, v18
	v_and_b32_e32 v76, 15, v21
	v_lshlrev_b32_e32 v76, 4, v76
	v_and_b32_e32 v77, -16, v21
	v_lshl_add_u32 v76, v77, 11, v76
	v_mul_u32_u24_e32 v77, 30, v64
	v_add_u32_e32 v76, v76, v77
	v_add_u32_e32 v76, 0x3a70000, v76
	v_mov_b32_e32 v77, 0
	v_add_u32_e32 v16, 0x4100, v21
	v_lshlrev_b64 v[22:23], 12, v[18:19]
	v_lshlrev_b64 v[18:19], 11, v[18:19]
	v_ashrrev_i32_e32 v17, 31, v16
	v_lshl_add_u64 v[74:75], v[18:19], 0, s[0:1]
	v_lshlrev_b64 v[18:19], 12, v[16:17]
	v_lshlrev_b64 v[16:17], 11, v[16:17]
	v_lshl_add_u64 v[80:81], v[16:17], 0, s[0:1]
	v_add_u32_e32 v16, 0x4080, v21
	v_ashrrev_i32_e32 v17, 31, v16
	v_mov_b32_e32 v67, 0
	v_or_b32_e32 v20, 0x200, v64
	v_lshl_add_u64 v[78:79], s[56:57], 0, v[18:19]
	v_lshlrev_b64 v[18:19], 12, v[16:17]
	v_lshlrev_b64 v[16:17], 11, v[16:17]
	v_add_u32_e32 v89, 0x3e00, v21
	v_mov_b32_e32 v69, v67
	v_lshl_add_u64 v[72:73], s[56:57], 0, v[22:23]
	v_lshl_add_u64 v[82:83], s[56:57], 0, v[18:19]
	v_lshl_add_u64 v[84:85], v[16:17], 0, s[0:1]
	s_mov_b64 s[28:29], 0
	s_movk_i32 s12, 0x4000
	s_movk_i32 s13, 0x3f80
	s_movk_i32 s33, 0x3f00
	s_mov_b32 s38, 0x3a800000
	s_mov_b32 s39, 0x800000
	s_movk_i32 s60, 0x6000
	s_mov_b64 s[44:45], 0x4000
	s_mov_b64 s[46:47], 0x3000
	s_mov_b64 s[48:49], 0x400
	v_lshlrev_b32_e32 v86, 2, v20
	v_mov_b32_e32 v88, 0x358637bd
	s_movk_i32 s61, 0x3e80
	s_mov_b64 s[50:51], 0x200000
	s_movk_i32 s64, 0x3e7f
	s_mov_b64 s[52:53], s[58:59]
	s_branch .LBB0_637

; __device__ __forceinline__ int fresh_tid() { int t = threadIdx.x; asm volatile("" : "+v"(t)); return t; }
; __device__ __forceinline__ unsigned xb_add(unsigned* p, unsigned v) { return __hip_atomic_fetch_add(p, v, __ATOMIC_RELAXED, __HIP_MEMORY_SCOPE_AGENT); }
; __global__ __launch_bounds__(512, 2) void fwd_megakernel(Params p) {
;     ...
;           asm volatile("s_waitcnt vmcnt(0)" ::: "memory"); __syncthreads();
;           if (fresh_tid() == 0) xb_add(ready6, 1u); }
.LBB0_649:
	s_or_b64 exec, exec, s[36:37]
	s_waitcnt vmcnt(0)
	v_mov_b32_e32 v0, v224
	s_waitcnt lgkmcnt(0)
	s_barrier
	s_nop 0
	v_cmp_eq_u32_e32 vcc, 0, v0
	s_and_saveexec_b64 s[0:1], vcc
	s_cbranch_execz .LBB0_652
	s_mov_b64 s[4:5], exec
	v_mbcnt_lo_u32_b32 v0, s4, 0
	v_mbcnt_hi_u32_b32 v0, s5, v0
	v_cmp_eq_u32_e32 vcc, 0, v0
	s_and_b64 s[6:7], exec, vcc
	s_mov_b64 exec, s[6:7]
	s_cbranch_execz .LBB0_652
	s_mov_b64 exec, 0xff
	v_mbcnt_lo_u32_b32 v0, -1, 0
	v_lshlrev_b32_e32 v0, 8, v0
	v_mov_b32_e32 v1, 1
	global_atomic_add v0, v1, s[24:25]

; __device__ __forceinline__ int fresh_tid() { int t = threadIdx.x; asm volatile("" : "+v"(t)); return t; }
; __device__ __forceinline__ void spin_until(unsigned* p, unsigned need) { unsigned sp = 0; while (xb_ld(p) < need) { __builtin_amdgcn_s_sleep(1); if (++sp > (1u << 20)) break; } }
; __global__ __launch_bounds__(512, 2) void fwd_megakernel(Params p) {
;     ...
;       if (fresh_tid() == 0) { spin_until(ready6, 16u); __builtin_amdgcn_fence(__ATOMIC_ACQUIRE, "agent"); asm volatile("s_waitcnt vmcnt(0)" ::: "memory"); }
.LBB0_673:
	v_mov_b32_e32 v0, v224
	s_nop 0
	v_cmp_eq_u32_e32 vcc, 0, v0
	s_and_saveexec_b64 s[0:1], vcc
	s_cbranch_execz .LBB0_688
	s_mov_b32 s6, 0x100000
	s_and_b32 s7, s2, 7
	s_lshl_b32 s7, s7, 8
	v_mov_b32_e32 v0, s7
	s_branch .LBB0_677
